# attention QK block: one counted lgkmcnt wait per MFMA (each MFMA waits only for its own K fragment) instead of hipcc's clustered waits
# baseline (speedup 1.0000x reference)
.LBB0_684:
	s_add_i32 s8, s92, s10
	s_cmp_gt_u32 s8, 8
	s_cbranch_scc1 .LBB0_673
	s_and_b32 s9, s17, 0x6000
	s_add_i32 s20, s9, 0
	v_add_u32_e32 v14, s20, v110
	v_add_u32_e32 v68, v14, v111
	ds_read_b128 v[64:67], v68
	ds_read_b128 v[120:123], v68 offset:4096
	v_add_u32_e32 v68, v14, v112
	ds_read_b128 v[124:127], v68
	ds_read_b128 v[128:131], v68 offset:4096
	v_add_u32_e32 v68, v14, v113
	ds_read_b128 v[132:135], v68
	ds_read_b128 v[136:139], v68 offset:4096
	v_add_u32_e32 v14, v14, v114
	ds_read_b128 v[140:143], v14
	ds_read_b128 v[144:147], v14 offset:4096
	s_cmp_gt_u32 s8, 2
	s_waitcnt lgkmcnt(7)
	v_mfma_f32_32x32x16_bf16 v[80:95], v[64:67], v[2:5], v[48:63]
	s_waitcnt lgkmcnt(6)
	v_mfma_f32_32x32x16_bf16 v[64:79], v[120:123], v[2:5], v[48:63]
	s_waitcnt lgkmcnt(5)
	v_mfma_f32_32x32x16_bf16 v[80:95], v[124:127], v[6:9], v[80:95]
	s_waitcnt lgkmcnt(4)
	v_mfma_f32_32x32x16_bf16 v[64:79], v[128:131], v[6:9], v[64:79]
	s_waitcnt lgkmcnt(3)
	v_mfma_f32_32x32x16_bf16 v[80:95], v[132:135], v[10:13], v[80:95]
	s_waitcnt lgkmcnt(2)
	v_mfma_f32_32x32x16_bf16 v[64:79], v[136:139], v[10:13], v[64:79]
	s_waitcnt lgkmcnt(1)
	v_mfma_f32_32x32x16_bf16 v[80:95], v[140:143], v[96:99], v[80:95]
	s_waitcnt lgkmcnt(0)
	v_mfma_f32_32x32x16_bf16 v[64:79], v[144:147], v[96:99], v[64:79]
	s_cbranch_scc1 .LBB0_687
	ds_read2_b32 v[120:121], v119 offset0:58 offset1:59
	ds_read2_b32 v[122:123], v119 offset0:26 offset1:27
	ds_read2_b32 v[124:125], v119 offset0:56 offset1:57
	ds_read2_b32 v[126:127], v119 offset0:24 offset1:25
	ds_read2_b32 v[128:129], v119 offset0:50 offset1:51
	ds_read2_b32 v[130:131], v119 offset0:18 offset1:19
	ds_read2_b32 v[132:133], v119 offset0:48 offset1:49
	ds_read2_b32 v[134:135], v119 offset0:16 offset1:17
	ds_read2_b32 v[136:137], v119 offset0:42 offset1:43
	ds_read2_b32 v[138:139], v119 offset0:10 offset1:11
	ds_read2_b32 v[140:141], v119 offset0:40 offset1:41
	ds_read2_b32 v[142:143], v119 offset0:8 offset1:9
	ds_read2_b32 v[144:145], v119 offset0:34 offset1:35
	ds_read2_b32 v[146:147], v119 offset0:2 offset1:3
	ds_read2_b32 v[148:149], v119 offset0:32 offset1:33
	ds_read2_b32 v[150:151], v119 offset0:0 offset1:1
	s_nop 0
	s_waitcnt lgkmcnt(0)
	s_nop 8
	v_pk_add_f32 v[80:81], v[80:81], v[120:121] op_sel:[0,1] op_sel_hi:[1,0]
	v_pk_add_f32 v[64:65], v[64:65], v[122:123] op_sel:[0,1] op_sel_hi:[1,0]
	v_pk_add_f32 v[82:83], v[82:83], v[124:125] op_sel:[0,1] op_sel_hi:[1,0]
	v_pk_add_f32 v[66:67], v[66:67], v[126:127] op_sel:[0,1] op_sel_hi:[1,0]
	v_pk_add_f32 v[84:85], v[84:85], v[128:129] op_sel:[0,1] op_sel_hi:[1,0]
	v_pk_add_f32 v[68:69], v[68:69], v[130:131] op_sel:[0,1] op_sel_hi:[1,0]
	v_pk_add_f32 v[86:87], v[86:87], v[132:133] op_sel:[0,1] op_sel_hi:[1,0]
	v_pk_add_f32 v[70:71], v[70:71], v[134:135] op_sel:[0,1] op_sel_hi:[1,0]
	v_pk_add_f32 v[88:89], v[88:89], v[136:137] op_sel:[0,1] op_sel_hi:[1,0]
	v_pk_add_f32 v[72:73], v[72:73], v[138:139] op_sel:[0,1] op_sel_hi:[1,0]
	v_pk_add_f32 v[90:91], v[90:91], v[140:141] op_sel:[0,1] op_sel_hi:[1,0]
	v_pk_add_f32 v[74:75], v[74:75], v[142:143] op_sel:[0,1] op_sel_hi:[1,0]
	v_pk_add_f32 v[92:93], v[92:93], v[144:145] op_sel:[0,1] op_sel_hi:[1,0]
	v_pk_add_f32 v[76:77], v[76:77], v[146:147] op_sel:[0,1] op_sel_hi:[1,0]
	v_pk_add_f32 v[94:95], v[94:95], v[148:149] op_sel:[0,1] op_sel_hi:[1,0]
	v_pk_add_f32 v[78:79], v[78:79], v[150:151] op_sel:[0,1] op_sel_hi:[1,0]

.LBB0_742:
	s_cmp_gt_u32 s8, 8
	s_cbranch_scc1 .LBB0_731
	s_add_i32 s2, s5, 0xffffa000
	s_and_b32 s2, s2, 0x6000
	s_add_i32 s9, s2, 0
	v_add_u32_e32 v14, s9, v101
	v_add_u32_e32 v68, v14, v106
	ds_read_b128 v[64:67], v68
	ds_read_b128 v[116:119], v68 offset:4096
	v_add_u32_e32 v68, v14, v108
	ds_read_b128 v[120:123], v68
	ds_read_b128 v[124:127], v68 offset:4096
	v_add_u32_e32 v68, v14, v109
	ds_read_b128 v[128:131], v68
	ds_read_b128 v[132:135], v68 offset:4096
	v_add_u32_e32 v14, v14, v110
	ds_read_b128 v[136:139], v14
	ds_read_b128 v[140:143], v14 offset:4096
	s_cmp_gt_u32 s8, 2
	s_waitcnt lgkmcnt(7)
	v_mfma_f32_32x32x16_bf16 v[80:95], v[64:67], v[2:5], v[48:63]
	s_waitcnt lgkmcnt(6)
	v_mfma_f32_32x32x16_bf16 v[64:79], v[116:119], v[2:5], v[48:63]
	s_waitcnt lgkmcnt(5)
	v_mfma_f32_32x32x16_bf16 v[80:95], v[120:123], v[6:9], v[80:95]
	s_waitcnt lgkmcnt(4)
	v_mfma_f32_32x32x16_bf16 v[64:79], v[124:127], v[6:9], v[64:79]
	s_waitcnt lgkmcnt(3)
	v_mfma_f32_32x32x16_bf16 v[80:95], v[128:131], v[10:13], v[80:95]
	s_waitcnt lgkmcnt(2)
	v_mfma_f32_32x32x16_bf16 v[64:79], v[132:135], v[10:13], v[64:79]
	s_waitcnt lgkmcnt(1)
	v_mfma_f32_32x32x16_bf16 v[80:95], v[136:139], v[96:99], v[80:95]
	s_waitcnt lgkmcnt(0)
	v_mfma_f32_32x32x16_bf16 v[64:79], v[140:143], v[96:99], v[64:79]
	s_cbranch_scc1 .LBB0_745
	ds_read2_b32 v[116:117], v113 offset0:58 offset1:59
	ds_read2_b32 v[118:119], v113 offset0:26 offset1:27
	ds_read2_b32 v[120:121], v113 offset0:56 offset1:57
	ds_read2_b32 v[122:123], v113 offset0:24 offset1:25
	ds_read2_b32 v[124:125], v113 offset0:50 offset1:51
	ds_read2_b32 v[126:127], v113 offset0:18 offset1:19
	ds_read2_b32 v[128:129], v113 offset0:48 offset1:49
	ds_read2_b32 v[130:131], v113 offset0:16 offset1:17
	ds_read2_b32 v[132:133], v113 offset0:42 offset1:43
	ds_read2_b32 v[134:135], v113 offset0:10 offset1:11
	ds_read2_b32 v[136:137], v113 offset0:40 offset1:41
	ds_read2_b32 v[138:139], v113 offset0:8 offset1:9
	ds_read2_b32 v[140:141], v113 offset0:34 offset1:35
	ds_read2_b32 v[142:143], v113 offset0:2 offset1:3
	ds_read2_b32 v[144:145], v113 offset0:32 offset1:33
	ds_read2_b32 v[146:147], v113 offset0:0 offset1:1
	s_nop 0
	s_waitcnt lgkmcnt(0)
	s_nop 8
	v_pk_add_f32 v[80:81], v[80:81], v[116:117] op_sel:[0,1] op_sel_hi:[1,0]
	v_pk_add_f32 v[64:65], v[64:65], v[118:119] op_sel:[0,1] op_sel_hi:[1,0]
	v_pk_add_f32 v[82:83], v[82:83], v[120:121] op_sel:[0,1] op_sel_hi:[1,0]
	v_pk_add_f32 v[66:67], v[66:67], v[122:123] op_sel:[0,1] op_sel_hi:[1,0]
	v_pk_add_f32 v[84:85], v[84:85], v[124:125] op_sel:[0,1] op_sel_hi:[1,0]
	v_pk_add_f32 v[68:69], v[68:69], v[126:127] op_sel:[0,1] op_sel_hi:[1,0]
	v_pk_add_f32 v[86:87], v[86:87], v[128:129] op_sel:[0,1] op_sel_hi:[1,0]
	v_pk_add_f32 v[70:71], v[70:71], v[130:131] op_sel:[0,1] op_sel_hi:[1,0]
	v_pk_add_f32 v[88:89], v[88:89], v[132:133] op_sel:[0,1] op_sel_hi:[1,0]
	v_pk_add_f32 v[72:73], v[72:73], v[134:135] op_sel:[0,1] op_sel_hi:[1,0]
	v_pk_add_f32 v[90:91], v[90:91], v[136:137] op_sel:[0,1] op_sel_hi:[1,0]
	v_pk_add_f32 v[74:75], v[74:75], v[138:139] op_sel:[0,1] op_sel_hi:[1,0]
	v_pk_add_f32 v[92:93], v[92:93], v[140:141] op_sel:[0,1] op_sel_hi:[1,0]
	v_pk_add_f32 v[76:77], v[76:77], v[142:143] op_sel:[0,1] op_sel_hi:[1,0]
	v_pk_add_f32 v[94:95], v[94:95], v[144:145] op_sel:[0,1] op_sel_hi:[1,0]
	v_pk_add_f32 v[78:79], v[78:79], v[146:147] op_sel:[0,1] op_sel_hi:[1,0]

.LBB0_789:
	v_cndmask_b32_e64 v14, 0, 1, s[22:23]
	v_cmp_ne_u32_e64 s[40:41], 1, v14
	v_cndmask_b32_e64 v14, 0, 1, s[10:11]
	s_andn2_b64 vcc, exec, s[22:23]
	v_cmp_ne_u32_e64 s[42:43], 1, v14
	s_cbranch_vccnz .LBB0_801
	ds_read_b128 v[64:67], v156
	ds_read_b128 v[164:167], v156 offset:4096
	ds_read_b128 v[168:171], v155
	ds_read_b128 v[172:175], v155 offset:4096
	ds_read_b128 v[176:179], v154
	ds_read_b128 v[180:183], v154 offset:4096
	ds_read_b128 v[184:187], v153
	ds_read_b128 v[188:191], v153 offset:4096
	s_nop 0
	s_and_b64 vcc, exec, s[42:43]
	s_waitcnt lgkmcnt(7)
	v_mfma_f32_32x32x16_bf16 v[80:95], v[64:67], v[96:99], v[48:63]
	s_waitcnt lgkmcnt(6)
	v_mfma_f32_32x32x16_bf16 v[64:79], v[164:167], v[96:99], v[48:63]
	s_waitcnt lgkmcnt(5)
	v_mfma_f32_32x32x16_bf16 v[80:95], v[168:171], v[10:13], v[80:95]
	s_waitcnt lgkmcnt(4)
	v_mfma_f32_32x32x16_bf16 v[64:79], v[172:175], v[10:13], v[64:79]
	s_waitcnt lgkmcnt(3)
	v_mfma_f32_32x32x16_bf16 v[80:95], v[176:179], v[6:9], v[80:95]
	s_waitcnt lgkmcnt(2)
	v_mfma_f32_32x32x16_bf16 v[64:79], v[180:183], v[6:9], v[64:79]
	s_waitcnt lgkmcnt(1)
	v_mfma_f32_32x32x16_bf16 v[80:95], v[184:187], v[2:5], v[80:95]
	s_waitcnt lgkmcnt(0)
	v_mfma_f32_32x32x16_bf16 v[64:79], v[188:191], v[2:5], v[64:79]
	s_cbranch_vccnz .LBB0_792
	ds_read2_b32 v[164:165], v157 offset0:58 offset1:59
	ds_read2_b32 v[166:167], v157 offset0:26 offset1:27
	ds_read2_b32 v[168:169], v157 offset0:56 offset1:57
	ds_read2_b32 v[170:171], v157 offset0:24 offset1:25
	ds_read2_b32 v[172:173], v157 offset0:50 offset1:51
	ds_read2_b32 v[174:175], v157 offset0:18 offset1:19
	ds_read2_b32 v[176:177], v157 offset0:48 offset1:49
	ds_read2_b32 v[178:179], v157 offset0:16 offset1:17
	ds_read2_b32 v[180:181], v157 offset0:42 offset1:43
	ds_read2_b32 v[182:183], v157 offset0:10 offset1:11
	ds_read2_b32 v[184:185], v157 offset0:40 offset1:41
	ds_read2_b32 v[186:187], v157 offset0:8 offset1:9
	ds_read2_b32 v[188:189], v157 offset0:34 offset1:35
	ds_read2_b32 v[190:191], v157 offset0:2 offset1:3
	ds_read2_b32 v[192:193], v157 offset0:32 offset1:33
	ds_read2_b32 v[194:195], v157 offset0:0 offset1:1
	s_nop 0
	s_waitcnt lgkmcnt(0)
	s_nop 8
	v_pk_add_f32 v[80:81], v[80:81], v[164:165] op_sel:[0,1] op_sel_hi:[1,0]
	v_pk_add_f32 v[64:65], v[64:65], v[166:167] op_sel:[0,1] op_sel_hi:[1,0]
	v_pk_add_f32 v[82:83], v[82:83], v[168:169] op_sel:[0,1] op_sel_hi:[1,0]
	v_pk_add_f32 v[66:67], v[66:67], v[170:171] op_sel:[0,1] op_sel_hi:[1,0]
	v_pk_add_f32 v[84:85], v[84:85], v[172:173] op_sel:[0,1] op_sel_hi:[1,0]
	v_pk_add_f32 v[68:69], v[68:69], v[174:175] op_sel:[0,1] op_sel_hi:[1,0]
	v_pk_add_f32 v[86:87], v[86:87], v[176:177] op_sel:[0,1] op_sel_hi:[1,0]
	v_pk_add_f32 v[70:71], v[70:71], v[178:179] op_sel:[0,1] op_sel_hi:[1,0]
	v_pk_add_f32 v[88:89], v[88:89], v[180:181] op_sel:[0,1] op_sel_hi:[1,0]
	v_pk_add_f32 v[72:73], v[72:73], v[182:183] op_sel:[0,1] op_sel_hi:[1,0]
	v_pk_add_f32 v[90:91], v[90:91], v[184:185] op_sel:[0,1] op_sel_hi:[1,0]
	v_pk_add_f32 v[74:75], v[74:75], v[186:187] op_sel:[0,1] op_sel_hi:[1,0]
	v_pk_add_f32 v[92:93], v[92:93], v[188:189] op_sel:[0,1] op_sel_hi:[1,0]
	v_pk_add_f32 v[76:77], v[76:77], v[190:191] op_sel:[0,1] op_sel_hi:[1,0]
	v_pk_add_f32 v[94:95], v[94:95], v[192:193] op_sel:[0,1] op_sel_hi:[1,0]
	v_pk_add_f32 v[78:79], v[78:79], v[194:195] op_sel:[0,1] op_sel_hi:[1,0]

.LBB0_809:
	ds_read_b128 v[64:67], v158
	ds_read_b128 v[140:143], v158 offset:4096
	ds_read_b128 v[164:167], v159
	ds_read_b128 v[168:171], v159 offset:4096
	ds_read_b128 v[172:175], v160
	ds_read_b128 v[176:179], v160 offset:4096
	ds_read_b128 v[180:183], v161
	ds_read_b128 v[184:187], v161 offset:4096
	s_nop 0
	s_and_b64 vcc, exec, s[42:43]
	s_waitcnt lgkmcnt(7)
	v_mfma_f32_32x32x16_bf16 v[80:95], v[64:67], v[96:99], v[48:63]
	s_waitcnt lgkmcnt(6)
	v_mfma_f32_32x32x16_bf16 v[64:79], v[140:143], v[96:99], v[48:63]
	s_waitcnt lgkmcnt(5)
	v_mfma_f32_32x32x16_bf16 v[80:95], v[164:167], v[10:13], v[80:95]
	s_waitcnt lgkmcnt(4)
	v_mfma_f32_32x32x16_bf16 v[64:79], v[168:171], v[10:13], v[64:79]
	s_waitcnt lgkmcnt(3)
	v_mfma_f32_32x32x16_bf16 v[80:95], v[172:175], v[6:9], v[80:95]
	s_waitcnt lgkmcnt(2)
	v_mfma_f32_32x32x16_bf16 v[64:79], v[176:179], v[6:9], v[64:79]
	s_waitcnt lgkmcnt(1)
	v_mfma_f32_32x32x16_bf16 v[80:95], v[180:183], v[2:5], v[80:95]
	s_waitcnt lgkmcnt(0)
	v_mfma_f32_32x32x16_bf16 v[64:79], v[184:187], v[2:5], v[64:79]
	s_cbranch_vccnz .LBB0_811
	ds_read2_b32 v[140:141], v162 offset0:58 offset1:59
	ds_read2_b32 v[142:143], v162 offset0:26 offset1:27
	ds_read2_b32 v[164:165], v162 offset0:56 offset1:57
	ds_read2_b32 v[166:167], v162 offset0:24 offset1:25
	ds_read2_b32 v[168:169], v162 offset0:50 offset1:51
	ds_read2_b32 v[170:171], v162 offset0:18 offset1:19
	ds_read2_b32 v[172:173], v162 offset0:48 offset1:49
	ds_read2_b32 v[174:175], v162 offset0:16 offset1:17
	ds_read2_b32 v[176:177], v162 offset0:42 offset1:43
	ds_read2_b32 v[178:179], v162 offset0:10 offset1:11
	ds_read2_b32 v[180:181], v162 offset0:40 offset1:41
	ds_read2_b32 v[182:183], v162 offset0:8 offset1:9
	ds_read2_b32 v[184:185], v162 offset0:34 offset1:35
	ds_read2_b32 v[186:187], v162 offset0:2 offset1:3
	ds_read2_b32 v[188:189], v162 offset0:32 offset1:33
	ds_read2_b32 v[190:191], v162 offset0:0 offset1:1
	s_nop 0
	s_waitcnt lgkmcnt(0)
	s_nop 8
	v_pk_add_f32 v[80:81], v[80:81], v[140:141] op_sel:[0,1] op_sel_hi:[1,0]
	v_pk_add_f32 v[64:65], v[64:65], v[142:143] op_sel:[0,1] op_sel_hi:[1,0]
	v_pk_add_f32 v[82:83], v[82:83], v[164:165] op_sel:[0,1] op_sel_hi:[1,0]
	v_pk_add_f32 v[66:67], v[66:67], v[166:167] op_sel:[0,1] op_sel_hi:[1,0]
	v_pk_add_f32 v[84:85], v[84:85], v[168:169] op_sel:[0,1] op_sel_hi:[1,0]
	v_pk_add_f32 v[68:69], v[68:69], v[170:171] op_sel:[0,1] op_sel_hi:[1,0]
	v_pk_add_f32 v[86:87], v[86:87], v[172:173] op_sel:[0,1] op_sel_hi:[1,0]
	v_pk_add_f32 v[70:71], v[70:71], v[174:175] op_sel:[0,1] op_sel_hi:[1,0]
	v_pk_add_f32 v[88:89], v[88:89], v[176:177] op_sel:[0,1] op_sel_hi:[1,0]
	v_pk_add_f32 v[72:73], v[72:73], v[178:179] op_sel:[0,1] op_sel_hi:[1,0]
	v_pk_add_f32 v[90:91], v[90:91], v[180:181] op_sel:[0,1] op_sel_hi:[1,0]
	v_pk_add_f32 v[74:75], v[74:75], v[182:183] op_sel:[0,1] op_sel_hi:[1,0]
	v_pk_add_f32 v[92:93], v[92:93], v[184:185] op_sel:[0,1] op_sel_hi:[1,0]
	v_pk_add_f32 v[76:77], v[76:77], v[186:187] op_sel:[0,1] op_sel_hi:[1,0]
	v_pk_add_f32 v[94:95], v[94:95], v[188:189] op_sel:[0,1] op_sel_hi:[1,0]
	v_pk_add_f32 v[78:79], v[78:79], v[190:191] op_sel:[0,1] op_sel_hi:[1,0]

.LBB0_918:
	s_add_i32 s2, s92, s9
	s_add_i32 s2, s2, -4
	s_cmp_gt_u32 s2, 8
	s_cbranch_scc1 .LBB0_930
	s_and_b32 s3, s5, 0x6000
	s_add_i32 s9, s3, 0
	v_add_u32_e32 v14, s9, v106
	v_add_u32_e32 v68, v14, v107
	ds_read_b128 v[64:67], v68
	ds_read_b128 v[116:119], v68 offset:4096
	v_add_u32_e32 v68, v14, v108
	ds_read_b128 v[120:123], v68
	ds_read_b128 v[124:127], v68 offset:4096
	v_add_u32_e32 v68, v14, v109
	ds_read_b128 v[128:131], v68
	ds_read_b128 v[132:135], v68 offset:4096
	v_add_u32_e32 v14, v14, v110
	ds_read_b128 v[136:139], v14
	ds_read_b128 v[140:143], v14 offset:4096
	s_cmp_gt_u32 s2, 2
	s_waitcnt lgkmcnt(7)
	v_mfma_f32_32x32x16_bf16 v[80:95], v[64:67], v[2:5], v[48:63]
	s_waitcnt lgkmcnt(6)
	v_mfma_f32_32x32x16_bf16 v[64:79], v[116:119], v[2:5], v[48:63]
	s_waitcnt lgkmcnt(5)
	v_mfma_f32_32x32x16_bf16 v[80:95], v[120:123], v[6:9], v[80:95]
	s_waitcnt lgkmcnt(4)
	v_mfma_f32_32x32x16_bf16 v[64:79], v[124:127], v[6:9], v[64:79]
	s_waitcnt lgkmcnt(3)
	v_mfma_f32_32x32x16_bf16 v[80:95], v[128:131], v[10:13], v[80:95]
	s_waitcnt lgkmcnt(2)
	v_mfma_f32_32x32x16_bf16 v[64:79], v[132:135], v[10:13], v[64:79]
	s_waitcnt lgkmcnt(1)
	v_mfma_f32_32x32x16_bf16 v[80:95], v[136:139], v[96:99], v[80:95]
	s_waitcnt lgkmcnt(0)
	v_mfma_f32_32x32x16_bf16 v[64:79], v[140:143], v[96:99], v[64:79]
	s_cbranch_scc1 .LBB0_921
	ds_read2_b32 v[116:117], v114 offset0:58 offset1:59
	ds_read2_b32 v[118:119], v114 offset0:26 offset1:27
	ds_read2_b32 v[120:121], v114 offset0:56 offset1:57
	ds_read2_b32 v[122:123], v114 offset0:24 offset1:25
	ds_read2_b32 v[124:125], v114 offset0:50 offset1:51
	ds_read2_b32 v[126:127], v114 offset0:18 offset1:19
	ds_read2_b32 v[128:129], v114 offset0:48 offset1:49
	ds_read2_b32 v[130:131], v114 offset0:16 offset1:17
	ds_read2_b32 v[132:133], v114 offset0:42 offset1:43
	ds_read2_b32 v[134:135], v114 offset0:10 offset1:11
	ds_read2_b32 v[136:137], v114 offset0:40 offset1:41
	ds_read2_b32 v[138:139], v114 offset0:8 offset1:9
	ds_read2_b32 v[140:141], v114 offset0:34 offset1:35
	ds_read2_b32 v[142:143], v114 offset0:2 offset1:3
	ds_read2_b32 v[144:145], v114 offset0:32 offset1:33
	ds_read2_b32 v[146:147], v114 offset0:0 offset1:1
	s_nop 0
	s_waitcnt lgkmcnt(0)
	s_nop 8
	v_pk_add_f32 v[80:81], v[80:81], v[116:117] op_sel:[0,1] op_sel_hi:[1,0]
	v_pk_add_f32 v[64:65], v[64:65], v[118:119] op_sel:[0,1] op_sel_hi:[1,0]
	v_pk_add_f32 v[82:83], v[82:83], v[120:121] op_sel:[0,1] op_sel_hi:[1,0]
	v_pk_add_f32 v[66:67], v[66:67], v[122:123] op_sel:[0,1] op_sel_hi:[1,0]
	v_pk_add_f32 v[84:85], v[84:85], v[124:125] op_sel:[0,1] op_sel_hi:[1,0]
	v_pk_add_f32 v[68:69], v[68:69], v[126:127] op_sel:[0,1] op_sel_hi:[1,0]
	v_pk_add_f32 v[86:87], v[86:87], v[128:129] op_sel:[0,1] op_sel_hi:[1,0]
	v_pk_add_f32 v[70:71], v[70:71], v[130:131] op_sel:[0,1] op_sel_hi:[1,0]
	v_pk_add_f32 v[88:89], v[88:89], v[132:133] op_sel:[0,1] op_sel_hi:[1,0]
	v_pk_add_f32 v[72:73], v[72:73], v[134:135] op_sel:[0,1] op_sel_hi:[1,0]
	v_pk_add_f32 v[90:91], v[90:91], v[136:137] op_sel:[0,1] op_sel_hi:[1,0]
	v_pk_add_f32 v[74:75], v[74:75], v[138:139] op_sel:[0,1] op_sel_hi:[1,0]
	v_pk_add_f32 v[92:93], v[92:93], v[140:141] op_sel:[0,1] op_sel_hi:[1,0]
	v_pk_add_f32 v[76:77], v[76:77], v[142:143] op_sel:[0,1] op_sel_hi:[1,0]
	v_pk_add_f32 v[94:95], v[94:95], v[144:145] op_sel:[0,1] op_sel_hi:[1,0]
	v_pk_add_f32 v[78:79], v[78:79], v[146:147] op_sel:[0,1] op_sel_hi:[1,0]

.LBB0_946:
	v_cndmask_b32_e64 v14, 0, 1, s[22:23]
	v_cmp_ne_u32_e64 s[38:39], 1, v14
	v_cndmask_b32_e64 v14, 0, 1, s[10:11]
	s_andn2_b64 vcc, exec, s[22:23]
	v_cmp_ne_u32_e64 s[40:41], 1, v14
	s_cbranch_vccnz .LBB0_958
	ds_read_b128 v[64:67], v156
	ds_read_b128 v[164:167], v156 offset:4096
	ds_read_b128 v[168:171], v155
	ds_read_b128 v[172:175], v155 offset:4096
	ds_read_b128 v[176:179], v154
	ds_read_b128 v[180:183], v154 offset:4096
	ds_read_b128 v[184:187], v153
	ds_read_b128 v[188:191], v153 offset:4096
	s_nop 0
	s_and_b64 vcc, exec, s[40:41]
	s_waitcnt lgkmcnt(7)
	v_mfma_f32_32x32x16_bf16 v[80:95], v[64:67], v[96:99], v[48:63]
	s_waitcnt lgkmcnt(6)
	v_mfma_f32_32x32x16_bf16 v[64:79], v[164:167], v[96:99], v[48:63]
	s_waitcnt lgkmcnt(5)
	v_mfma_f32_32x32x16_bf16 v[80:95], v[168:171], v[10:13], v[80:95]
	s_waitcnt lgkmcnt(4)
	v_mfma_f32_32x32x16_bf16 v[64:79], v[172:175], v[10:13], v[64:79]
	s_waitcnt lgkmcnt(3)
	v_mfma_f32_32x32x16_bf16 v[80:95], v[176:179], v[6:9], v[80:95]
	s_waitcnt lgkmcnt(2)
	v_mfma_f32_32x32x16_bf16 v[64:79], v[180:183], v[6:9], v[64:79]
	s_waitcnt lgkmcnt(1)
	v_mfma_f32_32x32x16_bf16 v[80:95], v[184:187], v[2:5], v[80:95]
	s_waitcnt lgkmcnt(0)
	v_mfma_f32_32x32x16_bf16 v[64:79], v[188:191], v[2:5], v[64:79]
	s_cbranch_vccnz .LBB0_949
	ds_read2_b32 v[164:165], v157 offset0:58 offset1:59
	ds_read2_b32 v[166:167], v157 offset0:26 offset1:27
	ds_read2_b32 v[168:169], v157 offset0:56 offset1:57
	ds_read2_b32 v[170:171], v157 offset0:24 offset1:25
	ds_read2_b32 v[172:173], v157 offset0:50 offset1:51
	ds_read2_b32 v[174:175], v157 offset0:18 offset1:19
	ds_read2_b32 v[176:177], v157 offset0:48 offset1:49
	ds_read2_b32 v[178:179], v157 offset0:16 offset1:17
	ds_read2_b32 v[180:181], v157 offset0:42 offset1:43
	ds_read2_b32 v[182:183], v157 offset0:10 offset1:11
	ds_read2_b32 v[184:185], v157 offset0:40 offset1:41
	ds_read2_b32 v[186:187], v157 offset0:8 offset1:9
	ds_read2_b32 v[188:189], v157 offset0:34 offset1:35
	ds_read2_b32 v[190:191], v157 offset0:2 offset1:3
	ds_read2_b32 v[192:193], v157 offset0:32 offset1:33
	ds_read2_b32 v[194:195], v157 offset0:0 offset1:1
	s_nop 0
	s_waitcnt lgkmcnt(0)
	s_nop 8
	v_pk_add_f32 v[80:81], v[80:81], v[164:165] op_sel:[0,1] op_sel_hi:[1,0]
	v_pk_add_f32 v[64:65], v[64:65], v[166:167] op_sel:[0,1] op_sel_hi:[1,0]
	v_pk_add_f32 v[82:83], v[82:83], v[168:169] op_sel:[0,1] op_sel_hi:[1,0]
	v_pk_add_f32 v[66:67], v[66:67], v[170:171] op_sel:[0,1] op_sel_hi:[1,0]
	v_pk_add_f32 v[84:85], v[84:85], v[172:173] op_sel:[0,1] op_sel_hi:[1,0]
	v_pk_add_f32 v[68:69], v[68:69], v[174:175] op_sel:[0,1] op_sel_hi:[1,0]
	v_pk_add_f32 v[86:87], v[86:87], v[176:177] op_sel:[0,1] op_sel_hi:[1,0]
	v_pk_add_f32 v[70:71], v[70:71], v[178:179] op_sel:[0,1] op_sel_hi:[1,0]
	v_pk_add_f32 v[88:89], v[88:89], v[180:181] op_sel:[0,1] op_sel_hi:[1,0]
	v_pk_add_f32 v[72:73], v[72:73], v[182:183] op_sel:[0,1] op_sel_hi:[1,0]
	v_pk_add_f32 v[90:91], v[90:91], v[184:185] op_sel:[0,1] op_sel_hi:[1,0]
	v_pk_add_f32 v[74:75], v[74:75], v[186:187] op_sel:[0,1] op_sel_hi:[1,0]
	v_pk_add_f32 v[92:93], v[92:93], v[188:189] op_sel:[0,1] op_sel_hi:[1,0]
	v_pk_add_f32 v[76:77], v[76:77], v[190:191] op_sel:[0,1] op_sel_hi:[1,0]
	v_pk_add_f32 v[94:95], v[94:95], v[192:193] op_sel:[0,1] op_sel_hi:[1,0]
	v_pk_add_f32 v[78:79], v[78:79], v[194:195] op_sel:[0,1] op_sel_hi:[1,0]

.LBB0_966:
	ds_read_b128 v[64:67], v158
	ds_read_b128 v[140:143], v158 offset:4096
	ds_read_b128 v[164:167], v159
	ds_read_b128 v[168:171], v159 offset:4096
	ds_read_b128 v[172:175], v160
	ds_read_b128 v[176:179], v160 offset:4096
	ds_read_b128 v[180:183], v161
	ds_read_b128 v[184:187], v161 offset:4096
	s_nop 0
	s_and_b64 vcc, exec, s[40:41]
	s_waitcnt lgkmcnt(7)
	v_mfma_f32_32x32x16_bf16 v[80:95], v[64:67], v[96:99], v[48:63]
	s_waitcnt lgkmcnt(6)
	v_mfma_f32_32x32x16_bf16 v[64:79], v[140:143], v[96:99], v[48:63]
	s_waitcnt lgkmcnt(5)
	v_mfma_f32_32x32x16_bf16 v[80:95], v[164:167], v[10:13], v[80:95]
	s_waitcnt lgkmcnt(4)
	v_mfma_f32_32x32x16_bf16 v[64:79], v[168:171], v[10:13], v[64:79]
	s_waitcnt lgkmcnt(3)
	v_mfma_f32_32x32x16_bf16 v[80:95], v[172:175], v[6:9], v[80:95]
	s_waitcnt lgkmcnt(2)
	v_mfma_f32_32x32x16_bf16 v[64:79], v[176:179], v[6:9], v[64:79]
	s_waitcnt lgkmcnt(1)
	v_mfma_f32_32x32x16_bf16 v[80:95], v[180:183], v[2:5], v[80:95]
	s_waitcnt lgkmcnt(0)
	v_mfma_f32_32x32x16_bf16 v[64:79], v[184:187], v[2:5], v[64:79]
	s_cbranch_vccnz .LBB0_968
	ds_read2_b32 v[140:141], v162 offset0:58 offset1:59
	ds_read2_b32 v[142:143], v162 offset0:26 offset1:27
	ds_read2_b32 v[164:165], v162 offset0:56 offset1:57
	ds_read2_b32 v[166:167], v162 offset0:24 offset1:25
	ds_read2_b32 v[168:169], v162 offset0:50 offset1:51
	ds_read2_b32 v[170:171], v162 offset0:18 offset1:19
	ds_read2_b32 v[172:173], v162 offset0:48 offset1:49
	ds_read2_b32 v[174:175], v162 offset0:16 offset1:17
	ds_read2_b32 v[176:177], v162 offset0:42 offset1:43
	ds_read2_b32 v[178:179], v162 offset0:10 offset1:11
	ds_read2_b32 v[180:181], v162 offset0:40 offset1:41
	ds_read2_b32 v[182:183], v162 offset0:8 offset1:9
	ds_read2_b32 v[184:185], v162 offset0:34 offset1:35
	ds_read2_b32 v[186:187], v162 offset0:2 offset1:3
	ds_read2_b32 v[188:189], v162 offset0:32 offset1:33
	ds_read2_b32 v[190:191], v162 offset0:0 offset1:1
	s_nop 0
	s_waitcnt lgkmcnt(0)
	s_nop 8
	v_pk_add_f32 v[80:81], v[80:81], v[140:141] op_sel:[0,1] op_sel_hi:[1,0]
	v_pk_add_f32 v[64:65], v[64:65], v[142:143] op_sel:[0,1] op_sel_hi:[1,0]
	v_pk_add_f32 v[82:83], v[82:83], v[164:165] op_sel:[0,1] op_sel_hi:[1,0]
	v_pk_add_f32 v[66:67], v[66:67], v[166:167] op_sel:[0,1] op_sel_hi:[1,0]
	v_pk_add_f32 v[84:85], v[84:85], v[168:169] op_sel:[0,1] op_sel_hi:[1,0]
	v_pk_add_f32 v[68:69], v[68:69], v[170:171] op_sel:[0,1] op_sel_hi:[1,0]
	v_pk_add_f32 v[86:87], v[86:87], v[172:173] op_sel:[0,1] op_sel_hi:[1,0]
	v_pk_add_f32 v[70:71], v[70:71], v[174:175] op_sel:[0,1] op_sel_hi:[1,0]
	v_pk_add_f32 v[88:89], v[88:89], v[176:177] op_sel:[0,1] op_sel_hi:[1,0]
	v_pk_add_f32 v[72:73], v[72:73], v[178:179] op_sel:[0,1] op_sel_hi:[1,0]
	v_pk_add_f32 v[90:91], v[90:91], v[180:181] op_sel:[0,1] op_sel_hi:[1,0]
	v_pk_add_f32 v[74:75], v[74:75], v[182:183] op_sel:[0,1] op_sel_hi:[1,0]
	v_pk_add_f32 v[92:93], v[92:93], v[184:185] op_sel:[0,1] op_sel_hi:[1,0]
	v_pk_add_f32 v[76:77], v[76:77], v[186:187] op_sel:[0,1] op_sel_hi:[1,0]
	v_pk_add_f32 v[94:95], v[94:95], v[188:189] op_sel:[0,1] op_sel_hi:[1,0]
	v_pk_add_f32 v[78:79], v[78:79], v[190:191] op_sel:[0,1] op_sel_hi:[1,0]
